# MoBA loops: QK MFMAs issued before the V staging stores (K first, then V); on top of fragment-major K + pipelined P6 epilogue
# baseline (speedup 1.0000x reference)
; #define B_ADV(n_, T_, ok_) do { const int cnt_ = ((n_) == qblk) ? own_tiles : 8; if (++(T_) >= cnt_) { const unsigned rest_ = uni & ~((2u << (n_)) - 1u); if (rest_) { (n_) = __builtin_ctz(rest_); (T_) = 0; } else (ok_) = false; } } while (0)
; DI void tile_gload(TileRegs& t, const bf16_t* K, const bf16_t* V, int kbase, int kstride, int lane) {
;     const int row0 = lane >> 3, ch = lane & 7;
; #pragma unroll
;     for (int i = 0; i < 4; ++i) {
;         const unsigned off = (unsigned)((kbase + kstride * (row0 + 8 * i)) * 128 + ch * 16);
;         t.k[i] = *(const u32x4*)((const unsigned char*)K + off); t.v[i] = *(const u32x4*)((const unsigned char*)V + off);
;     }
; DI void attn_b_item(unsigned char* ws, LAS unsigned char* buf, LAS unsigned char* qbuf, LAS unsigned* tbl, LAS float* km  , int bh, int qblk, int w4, int lane) {
;     ...
;         int nc = __builtin_ctz(uni), Tc = 0;
;         tile_gload(tr, K, V, nc * 256, 1, lane);
;         for (;;) {
;             tile_lds_write(buf, tr, lane);
;             int nl = nc, Tl = Tc; bool okl = true; B_ADV(nl, Tl, okl);
;             if (okl) tile_gload(tr, K, V, nl * 256 + 32 * Tl, 1, lane);
.LBB0_562:
	s_lshl_b32 s16, s81, 1
	s_add_u32 s78, s38, s16
	s_addc_u32 s79, s39, 0
	s_add_u32 s80, s64, s16
	s_addc_u32 s81, s65, 0
	s_andn2_b32 s16, s18, s56
	s_lshl_b32 s17, 1, s57
	s_or_b32 s85, s16, s17
	s_ff1_i32_b32 s20, s85
	s_lshl_b32 s16, s20, 8
	v_mbcnt_hi_u32_b32 v206, -1, v224
	v_lshlrev_b32_e32 v206, 4, v206
	s_lshl_b32 s16, s16, 7
	v_add_u32_e32 v207, s16, v206
	global_load_dwordx4 v[148:151], v207, s[78:79]
	global_load_dwordx4 v[156:159], v207, s[78:79] offset:1024
	global_load_dwordx4 v[164:167], v207, s[78:79] offset:2048
	global_load_dwordx4 v[172:175], v207, s[78:79] offset:3072
	global_load_dwordx4 v[152:155], v207, s[80:81]
	global_load_dwordx4 v[160:163], v207, s[80:81] offset:1024
	global_load_dwordx4 v[168:171], v207, s[80:81] offset:2048
	global_load_dwordx4 v[176:179], v207, s[80:81] offset:3072
	s_lshl_b32 s86, s82, 1
	v_xor_b32_e32 v64, 0x80000000, v247
	v_mov_b32_e32 v183, 0
	s_add_i32 s87, s86, 2
	v_mov_b32_e32 v65, v64
	v_mov_b32_e32 v66, v64
	v_mov_b32_e32 v67, v64
	v_mov_b32_e32 v68, v64
	v_mov_b32_e32 v69, v64
	v_mov_b32_e32 v70, v64
	v_mov_b32_e32 v71, v64
	v_mov_b32_e32 v72, v64
	v_mov_b32_e32 v73, v64
	v_mov_b32_e32 v74, v64
	v_mov_b32_e32 v75, v64
	v_mov_b32_e32 v76, v64
	v_mov_b32_e32 v77, v64
	v_mov_b32_e32 v78, v64
	v_mov_b32_e32 v79, v64
	s_mov_b32 s21, 0
	v_mov_b32_e32 v189, 0
	v_mov_b32_e32 v48, 0
	v_mov_b32_e32 v49, v183
	v_mov_b32_e32 v50, v183
	v_mov_b32_e32 v51, v183
	v_mov_b32_e32 v52, v183
	v_mov_b32_e32 v53, v183
	v_mov_b32_e32 v54, v183
	v_mov_b32_e32 v55, v183
	v_mov_b32_e32 v56, v183
	v_mov_b32_e32 v57, v183
	v_mov_b32_e32 v58, v183
	v_mov_b32_e32 v59, v183
	v_mov_b32_e32 v60, v183
	v_mov_b32_e32 v61, v183
	v_mov_b32_e32 v62, v183
	v_mov_b32_e32 v63, v183
	v_mov_b32_e32 v32, 0
	v_mov_b32_e32 v33, v183
	v_mov_b32_e32 v34, v183
	v_mov_b32_e32 v35, v183
	v_mov_b32_e32 v36, v183
	v_mov_b32_e32 v37, v183
	v_mov_b32_e32 v38, v183
	v_mov_b32_e32 v39, v183
	v_mov_b32_e32 v40, v183
	v_mov_b32_e32 v41, v183
	v_mov_b32_e32 v42, v183
	v_mov_b32_e32 v43, v183
	v_mov_b32_e32 v44, v183
	v_mov_b32_e32 v45, v183
	v_mov_b32_e32 v46, v183
	v_mov_b32_e32 v47, v183
	v_mov_b32_e32 v0, 0
	v_mov_b32_e32 v1, v183
	v_mov_b32_e32 v2, v183
	v_mov_b32_e32 v3, v183
	v_mov_b32_e32 v4, v183
	v_mov_b32_e32 v5, v183
	v_mov_b32_e32 v6, v183
	v_mov_b32_e32 v7, v183
	v_mov_b32_e32 v8, v183
	v_mov_b32_e32 v9, v183
	v_mov_b32_e32 v10, v183
	v_mov_b32_e32 v11, v183
	v_mov_b32_e32 v12, v183
	v_mov_b32_e32 v13, v183
	v_mov_b32_e32 v14, v183
	v_mov_b32_e32 v15, v183
	v_mov_b32_e32 v16, 0
	v_mov_b32_e32 v17, v183
	v_mov_b32_e32 v18, v183
	v_mov_b32_e32 v19, v183
	v_mov_b32_e32 v20, v183
	v_mov_b32_e32 v21, v183
	v_mov_b32_e32 v22, v183
	v_mov_b32_e32 v23, v183
	v_mov_b32_e32 v24, v183
	v_mov_b32_e32 v25, v183
	v_mov_b32_e32 v26, v183
	v_mov_b32_e32 v27, v183
	v_mov_b32_e32 v28, v183
	v_mov_b32_e32 v29, v183
	v_mov_b32_e32 v30, v183
	v_mov_b32_e32 v31, v183
.LBB0_563:
	s_cmp_eq_u32 s20, s57
	s_cselect_b64 s[16:17], -1, 0
	s_and_b64 s[18:19], s[16:17], exec
	s_cselect_b32 s88, s87, 8
	s_lshl_b32 s18, -2, s20
	s_add_i32 s90, s21, 1
	s_and_b32 s82, s18, s85
	s_cmp_lg_u32 s82, 0
	s_cselect_b64 s[18:19], -1, 0
	s_ff1_i32_b32 s89, s82
	s_and_b64 s[82:83], s[18:19], exec
	s_cselect_b32 s91, s89, s20
	s_cselect_b32 vcc_lo, 0, s90
	s_cmp_lt_i32 s90, s88
	s_cselect_b64 s[82:83], -1, 0
	s_and_b64 s[88:89], s[82:83], exec
	s_cselect_b32 s88, s90, vcc_lo
	s_cselect_b32 s89, s20, s91
	s_nor_b64 s[82:83], s[82:83], s[18:19]
	v_add_u32_e32 v223, s71, v225
	s_and_b64 vcc, exec, s[82:83]
	s_lshl_b32 s18, s89, 8
	s_lshl_b32 s19, s88, 5
	s_add_i32 s18, s18, s19
	s_lshl_b32 s18, s18, 7
	v_add_u32_e32 v207, s18, v206
; #define MFMA32(a, b, c) __builtin_amdgcn_mfma_f32_32x32x16_bf16((a), (b), (c), 0, 0, 0)
; #define B_ADV(n_, T_, ok_) do { const int cnt_ = ((n_) == qblk) ? own_tiles : 8; if (++(T_) >= cnt_) { const unsigned rest_ = uni & ~((2u << (n_)) - 1u); if (rest_) { (n_) = __builtin_ctz(rest_); (T_) = 0; } else (ok_) = false; } } while (0)
; DI void core2(QT& a, QT& b, LAS unsigned char* buf, int dist0a, int dist0b, int kstride, int hi, bool elem, bool oka, bool okb, float m0, int lane) {
;     ...
;     {
;         const float c = -m0;
;         const f32x16 cinit = {c, c, c, c, c, c, c, c, c, c, c, c, c, c, c, c};
;         const bf16x8 kf = lds_frag(buf + r * TROW + h * 16); sa = MFMA32(kf, a.qf[0], cinit); sb = MFMA32(kf, b.qf[0], cinit);
;     }
; #pragma unroll
;     for (int ks = 1; ks < 4; ++ks) { const bf16x8 kf = lds_frag(buf + r * TROW + (2 * ks + h) * 16); sa = MFMA32(kf, a.qf[ks], sa); sb = MFMA32(kf, b.qf[ks], sb); }
; DI void attn_b_item(unsigned char* ws, LAS unsigned char* buf, LAS unsigned char* qbuf, LAS unsigned* tbl, LAS float* km  , int bh, int qblk, int w4, int lane) {
;     ...
;             tile_lds_write(buf, tr, lane);
;             int nl = nc, Tl = Tc; bool okl = true; B_ADV(nl, Tl, okl);
;             if (okl) tile_gload(tr, K, V, nl * 256 + 32 * Tl, 1, lane);
.LBB0_565:
	s_lshl_b32 s18, s20, 8
	s_lshl_b32 s19, s21, 5
	s_add_i32 s18, s18, s19
	s_cmp_ge_i32 s21, s86
	v_or_b32_e32 v112, s18, v186
	s_cselect_b64 s[18:19], -1, 0
	s_and_b64 s[90:91], s[16:17], s[18:19]
	v_cndmask_b32_e64 v113, 0, 1, s[90:91]
	s_waitcnt vmcnt(7)
	v_mfma_f32_32x32x16_bf16 v[96:111], v[148:151], v[116:119], v[64:79]
	v_cmp_ne_u32_e64 s[18:19], 1, v113
	s_andn2_b64 vcc, exec, s[90:91]
	v_mfma_f32_32x32x16_bf16 v[80:95], v[148:151], v[132:135], v[64:79]
	s_waitcnt vmcnt(6)
	v_mfma_f32_32x32x16_bf16 v[96:111], v[156:159], v[120:123], v[96:111]
	v_mfma_f32_32x32x16_bf16 v[80:95], v[156:159], v[136:139], v[80:95]
	s_waitcnt vmcnt(5)
	v_mfma_f32_32x32x16_bf16 v[96:111], v[164:167], v[124:127], v[96:111]
	v_mfma_f32_32x32x16_bf16 v[80:95], v[164:167], v[140:143], v[80:95]
	s_waitcnt vmcnt(4)
	v_mfma_f32_32x32x16_bf16 v[96:111], v[172:175], v[128:131], v[96:111]
	v_mfma_f32_32x32x16_bf16 v[80:95], v[172:175], v[144:147], v[80:95]
	global_load_dwordx4 v[148:151], v207, s[78:79]
	global_load_dwordx4 v[156:159], v207, s[78:79] offset:1024
	global_load_dwordx4 v[164:167], v207, s[78:79] offset:2048
	global_load_dwordx4 v[172:175], v207, s[78:79] offset:3072
	s_waitcnt vmcnt(7)
	ds_write_b128 v223, v[152:155] offset:4608
	s_waitcnt vmcnt(6)
	ds_write_b128 v223, v[160:163] offset:5760
	s_waitcnt vmcnt(5)
	ds_write_b128 v223, v[168:171] offset:6912
	s_waitcnt vmcnt(4)
	ds_write_b128 v223, v[176:179] offset:8064
	global_load_dwordx4 v[152:155], v207, s[80:81]
	global_load_dwordx4 v[160:163], v207, s[80:81] offset:1024
	global_load_dwordx4 v[168:171], v207, s[80:81] offset:2048
	global_load_dwordx4 v[176:179], v207, s[80:81] offset:3072
	s_cbranch_vccnz .LBB0_567
	v_sub_u32_e32 v113, v246, v112
	s_nop 0
	v_cmp_lt_i32_e32 vcc, -1, v113
	v_add_u32_e32 v114, -3, v113
	s_nop 5
	v_cndmask_b32_e32 v96, v245, v96, vcc
	v_cmp_lt_i32_e32 vcc, 0, v113
	s_nop 1
	v_cndmask_b32_e32 v97, v245, v97, vcc
	v_cmp_lt_i32_e32 vcc, 1, v113
	s_nop 1
	v_cndmask_b32_e32 v98, v245, v98, vcc
	v_cmp_lt_i32_e32 vcc, -1, v114
	v_add_u32_e32 v114, -9, v113
	s_nop 0
	v_cndmask_b32_e32 v99, v245, v99, vcc
	v_cmp_lt_i32_e32 vcc, 7, v113
	s_nop 1
	v_cndmask_b32_e32 v100, v245, v100, vcc
	v_cmp_lt_i32_e32 vcc, -1, v114
	v_add_u32_e32 v114, -10, v113
	s_nop 0
	v_cndmask_b32_e32 v101, v245, v101, vcc
	v_cmp_lt_i32_e32 vcc, -1, v114
	v_add_u32_e32 v114, -11, v113
	s_nop 0
	v_cndmask_b32_e32 v102, v245, v102, vcc
	v_cmp_lt_i32_e32 vcc, -1, v114
	v_subrev_u32_e32 v114, 17, v113
	s_nop 0
	v_cndmask_b32_e32 v103, v245, v103, vcc
	v_cmp_lt_i32_e32 vcc, 15, v113
	s_nop 1
	v_cndmask_b32_e32 v104, v245, v104, vcc
	v_cmp_lt_i32_e32 vcc, -1, v114
	v_subrev_u32_e32 v114, 18, v113
	s_nop 0
	v_cndmask_b32_e32 v105, v245, v105, vcc
	v_cmp_lt_i32_e32 vcc, -1, v114
	v_subrev_u32_e32 v114, 19, v113
	s_nop 0
	v_cndmask_b32_e32 v106, v245, v106, vcc
	v_cmp_lt_i32_e32 vcc, -1, v114
	v_subrev_u32_e32 v114, 24, v113
	s_nop 0
	v_cndmask_b32_e32 v107, v245, v107, vcc
	v_cmp_lt_i32_e32 vcc, -1, v114
	v_subrev_u32_e32 v114, 25, v113
	s_nop 0
	v_cndmask_b32_e32 v108, v245, v108, vcc
	v_cmp_lt_i32_e32 vcc, -1, v114
	v_subrev_u32_e32 v114, 26, v113
	v_subrev_u32_e32 v113, 27, v113
	v_cndmask_b32_e32 v109, v245, v109, vcc
	v_cmp_lt_i32_e32 vcc, -1, v114
	s_nop 1
	v_cndmask_b32_e32 v110, v245, v110, vcc
	v_cmp_lt_i32_e32 vcc, -1, v113
	s_nop 1
	v_cndmask_b32_e32 v111, v245, v111, vcc

; DI void attn_b_item(unsigned char* ws, LAS unsigned char* buf, LAS unsigned char* qbuf, LAS unsigned* tbl, LAS float* km  , int bh, int qblk, int w4, int lane) {
;     ...
;     if (cmask) {
;         int n = __builtin_ctz(cmask);
;         tile_gload(tr, K, V, n * 256, 1, lane);
.LBB0_571:
	s_waitcnt vmcnt(0)
	s_cmp_eq_u32 s56, 0
	s_cbranch_scc1 .LBB0_519
	s_ff1_i32_b32 s88, s56
	v_mbcnt_hi_u32_b32 v193, -1, v224
	v_lshlrev_b32_e32 v191, 4, v193
	v_and_b32_e32 v190, 31, v193
	v_lshrrev_b32_e32 v192, 5, v193
	v_lshlrev_b32_e32 v190, 7, v190
	v_lshl_or_b32 v190, v192, 4, v190
	s_lshl_b32 s16, s88, 15
	v_add_u32_e32 v193, s16, v191
	v_add_u32_e32 v192, s16, v190
	global_load_dwordx4 v[116:119], v193, s[78:79]
	global_load_dwordx4 v[120:123], v193, s[78:79] offset:1024
	global_load_dwordx4 v[124:127], v193, s[78:79] offset:2048
	global_load_dwordx4 v[128:131], v193, s[78:79] offset:3072
	global_load_dwordx4 v[132:135], v193, s[80:81]
	global_load_dwordx4 v[136:139], v193, s[80:81] offset:1024
	global_load_dwordx4 v[140:143], v193, s[80:81] offset:2048
	global_load_dwordx4 v[144:147], v193, s[80:81] offset:3072
	s_lshl_b32 s16, s44, 19
	s_lshl_b32 s17, s84, 22
	s_or_b32 s16, s17, s16
	s_add_u32 s82, s50, s16
	s_addc_u32 s83, s51, 0

; #define LAS __attribute__((address_space(3)))
; #define MFMA32(a, b, c) __builtin_amdgcn_mfma_f32_32x32x16_bf16((a), (b), (c), 0, 0, 0)
; DI void core1g(ASt& st, const bf16x8 (&qf)[4], LAS unsigned char* buf, bool ok, float m0, int lane) {
;     const int r = lane & 31, h = lane >> 5;
;     f32x16 s;
;     {
;         const f32x16 zero = {0.f, 0.f, 0.f, 0.f, 0.f, 0.f, 0.f, 0.f, 0.f, 0.f, 0.f, 0.f, 0.f, 0.f, 0.f, 0.f};
;         const bf16x8 kf = lds_frag(buf + r * TROW + h * 16); s = MFMA32(kf, qf[0], zero);
;     }
; #pragma unroll
;     for (int ks = 1; ks < 4; ++ks) { const bf16x8 kf = lds_frag(buf + r * TROW + (2 * ks + h) * 16); s = MFMA32(kf, qf[ks], s); }
;     LAS unsigned char* vb = buf + 32 * TROW + (4 * h + ((lane & 15) >> 2)) * TROW + 32 * ((lane >> 4) & 1) + 8 * (lane & 3);
;     softmax_p<true>(st, s, 0, 0, 0, ok, false, m0);
;     bf16x8 p[2]; pack_p(p, s, ok);
; #pragma unroll
;     for (int s2 = 0; s2 < 2; ++s2) {
;         const bf16x8 v0 = load_vfrag1(vb, 0, s2), v1 = load_vfrag1(vb, 1, s2);
;         st.o0 = MFMA32(v0, p[s2], st.o0); st.o1 = MFMA32(v1, p[s2], st.o1);
;     }
; DI void attn_b_item(unsigned char* ws, LAS unsigned char* buf, LAS unsigned char* qbuf, LAS unsigned* tbl, LAS float* km  , int bh, int qblk, int w4, int lane) {
;     ...
; #pragma unroll 1
;             for (int T = 0; T < 8; ++T) {
;                 tile_lds_write(buf, tr, lane);
;                 if (T < 7) tile_gload(tr, K, V, n * 256 + 32 * (T + 1), 1, lane);
;                 else if (nn >= 0) tile_gload(tr, K, V, nn * 256, 1, lane);
;                 core1g(g, gq, buf, okg, m0, lane);
;             }
.Lg_off_done:
	s_add_i32 s88, s88, 0x1000
	s_cmpk_eq_u32 s88, 0x8000
	s_waitcnt vmcnt(7)
	v_mfma_f32_32x32x16_bf16 v[96:111], v[116:119], v[148:151], 0
	s_waitcnt vmcnt(6)
	v_mfma_f32_32x32x16_bf16 v[96:111], v[120:123], v[152:155], v[96:111]
	s_waitcnt vmcnt(5)
	v_mfma_f32_32x32x16_bf16 v[96:111], v[124:127], v[156:159], v[96:111]
	v_add_u32_e32 v193, s90, v191
	s_waitcnt vmcnt(4)
	v_mfma_f32_32x32x16_bf16 v[96:111], v[128:131], v[160:163], v[96:111]
	global_load_dwordx4 v[116:119], v193, s[78:79]
	global_load_dwordx4 v[120:123], v193, s[78:79] offset:1024
	global_load_dwordx4 v[124:127], v193, s[78:79] offset:2048
	global_load_dwordx4 v[128:131], v193, s[78:79] offset:3072
	s_waitcnt vmcnt(7)
	ds_write_b128 v223, v[132:135] offset:4608
	s_waitcnt vmcnt(6)
	ds_write_b128 v223, v[136:139] offset:5760
	s_waitcnt vmcnt(5)
	ds_write_b128 v223, v[140:143] offset:6912
	s_waitcnt vmcnt(4)
	ds_write_b128 v223, v[144:147] offset:8064
	global_load_dwordx4 v[132:135], v193, s[80:81]
	global_load_dwordx4 v[136:139], v193, s[80:81] offset:1024
	global_load_dwordx4 v[140:143], v193, s[80:81] offset:2048
	global_load_dwordx4 v[144:147], v193, s[80:81] offset:3072
	ds_read_b64_tr_b16 v[164:165], v222 offset:4608
	ds_read_b64_tr_b16 v[166:167], v222 offset:5760
	v_sub_f32_e32 v96, v96, v247
	v_sub_f32_e32 v97, v97, v247
	v_sub_f32_e32 v98, v98, v247
	v_sub_f32_e32 v99, v99, v247
	v_exp_f32_e32 v96, v96
	v_exp_f32_e32 v97, v97
	v_sub_f32_e32 v100, v100, v247
	v_sub_f32_e32 v101, v101, v247
	v_exp_f32_e32 v98, v98
	v_exp_f32_e32 v99, v99
	v_sub_f32_e32 v102, v102, v247
	v_sub_f32_e32 v103, v103, v247
	v_exp_f32_e32 v100, v100
	v_exp_f32_e32 v101, v101
	v_sub_f32_e32 v104, v104, v247
	v_sub_f32_e32 v105, v105, v247
	v_sub_f32_e32 v108, v108, v247
	v_sub_f32_e32 v109, v109, v247
	v_exp_f32_e32 v102, v102
	v_exp_f32_e32 v103, v103
	v_exp_f32_e32 v104, v104
	v_exp_f32_e32 v105, v105
	v_exp_f32_e32 v168, v108
	v_exp_f32_e32 v169, v109
	v_pk_add_f32 v[108:109], v[96:97], 0 op_sel_hi:[1,0]
	v_cvt_pk_bf16_f32 v96, v96, v97
	v_cvt_pk_bf16_f32 v97, v98, v99
	v_pk_add_f32 v[98:99], v[98:99], v[108:109]
	v_sub_f32_e32 v106, v106, v247
	v_pk_add_f32 v[98:99], v[100:101], v[98:99]
	v_sub_f32_e32 v107, v107, v247
	v_pk_add_f32 v[98:99], v[102:103], v[98:99]
	v_sub_f32_e32 v110, v110, v247
	v_pk_add_f32 v[108:109], v[104:105], v[98:99]
	v_cvt_pk_bf16_f32 v98, v100, v101
	v_cvt_pk_bf16_f32 v99, v102, v103
	ds_read_b64_tr_b16 v[102:103], v222 offset:5824
	ds_read_b64_tr_b16 v[100:101], v222 offset:4672
	v_sub_f32_e32 v111, v111, v247
	v_exp_f32_e32 v106, v106
	v_exp_f32_e32 v107, v107
	v_exp_f32_e32 v170, v110
	v_exp_f32_e32 v171, v111
	v_cndmask_b32_e64 v96, 0, v96, s[20:21]
	v_cndmask_b32_e64 v97, 0, v97, s[20:21]
	v_cndmask_b32_e64 v98, 0, v98, s[20:21]
	v_cndmask_b32_e64 v99, 0, v99, s[20:21]
	v_pk_add_f32 v[108:109], v[106:107], v[108:109]
	v_cvt_pk_bf16_f32 v104, v104, v105
	s_waitcnt lgkmcnt(2)
	v_mfma_f32_32x32x16_bf16 v[64:79], v[164:167], v[96:99], v[64:79]
	v_cvt_pk_bf16_f32 v105, v106, v107
	v_add_f32_e64 v164, v168, v108
	v_add_f32_e64 v165, v169, v109
	ds_read_b64_tr_b16 v[108:109], v222 offset:6912
	ds_read_b64_tr_b16 v[110:111], v222 offset:8064
	v_cndmask_b32_e64 v104, 0, v104, s[20:21]
	v_cndmask_b32_e64 v105, 0, v105, s[20:21]
	s_waitcnt lgkmcnt(2)
	v_mfma_f32_32x32x16_bf16 v[80:95], v[100:103], v[96:99], v[80:95]
	v_cvt_pk_bf16_f32 v96, v168, v169
	v_cndmask_b32_e64 v106, 0, v96, s[20:21]
	v_cvt_pk_bf16_f32 v96, v170, v171
	v_cndmask_b32_e64 v107, 0, v96, s[20:21]
	ds_read_b64_tr_b16 v[98:99], v222 offset:8128
	ds_read_b64_tr_b16 v[96:97], v222 offset:6976
	v_pk_add_f32 v[100:101], v[170:171], v[164:165]
	s_waitcnt lgkmcnt(2)
	v_mfma_f32_32x32x16_bf16 v[64:79], v[108:111], v[104:107], v[64:79]
	v_add_f32_e32 v100, v100, v101
	v_cndmask_b32_e64 v100, 0, v100, s[20:21]
	v_add_f32_e32 v112, v112, v100
	s_waitcnt lgkmcnt(0)
	v_mfma_f32_32x32x16_bf16 v[80:95], v[96:99], v[104:107], v[80:95]
	s_cbranch_scc1 .LBB0_589
	s_branch .LBB0_581
